# grid barrier: every arriving workgroup leader issues an early L2 write-back (not waited) before its arrival atomic
# baseline (speedup 1.0000x reference)
; __device__ __forceinline__ unsigned xb_ld(unsigned* p)              { return __hip_atomic_load(p, __ATOMIC_RELAXED, __HIP_MEMORY_SCOPE_AGENT); }
; __device__ __forceinline__ void xcd_barrier_complete(unsigned* bar, unsigned x, unsigned& nloc, unsigned& nx) {
;     const unsigned G = gridDim.x * gridDim.y * gridDim.z;
;     unsigned sum, cnt, mine, sp = 0u;
;     for (;;) {
;         sum = 0u; cnt = 0u; mine = 0u;
; #pragma unroll
;         for (unsigned j = 0; j < 16; ++j) { const unsigned c = xb_ld(&bar[XB_XCNT(j)]); sum += c; cnt += (c > 0u) ? 1u : 0u; mine = (j == x) ? c : mine; }
; __device__ __forceinline__ void xcd_barrier(const XcdBarrier& b, const bool leader) {
;     asm volatile("s_waitcnt vmcnt(0)" ::: "memory");
;     __syncthreads();
;     if (leader) {
;         unsigned* bar = b.bar;
;         __builtin_amdgcn_s_waitcnt(0);
;         unsigned nloc = b.st[0], nx = b.st[1];
;         if (nloc == 0u) { xcd_barrier_complete(bar, b.x, nloc, nx); b.st[0] = nloc; b.st[1] = nx; }
.LBB0_31:
	s_getreg_b32 s1, hwreg(HW_REG_XCC_ID, 0, 4)
	s_waitcnt vmcnt(0)
	v_cmp_eq_u32_e64 s[2:3], 0, v201
	s_barrier
	s_mov_b64 s[4:5], exec
	v_writelane_b32 v251, s2, 6
	s_nop 1
	v_writelane_b32 v251, s3, 7
	s_and_b64 s[2:3], s[4:5], s[2:3]
	s_mov_b64 exec, s[2:3]
	s_cbranch_execz .LBB0_83
	s_add_i32 s2, 0, 0x22000
	v_mov_b32_e32 v2, s2
	s_waitcnt vmcnt(0) expcnt(0) lgkmcnt(0)
	buffer_wbl2 sc1
	ds_read_b32 v4, v2
	s_add_i32 s2, 0, 0x22004
	v_mov_b32_e32 v2, s2
	ds_read_b32 v2, v2
	s_and_b32 s1, s1, 15
	s_waitcnt lgkmcnt(1)
	v_cmp_ne_u32_e32 vcc, 0, v4
	s_cbranch_vccnz .LBB0_47
	s_load_dwordx4 s[40:43], s[90:91], 0xa8
	s_mul_i32 s2, s71, s0
	s_mul_i32 s2, s2, s70
	s_mov_b32 s3, 1
	v_mov_b32_e32 v18, 0
	s_waitcnt lgkmcnt(0)
	s_add_u32 s8, s42, 0x1d798200
	s_addc_u32 s9, s43, 0
	s_add_u32 s10, s42, 0x1d798400
	s_addc_u32 s11, s43, 0
	s_add_u32 s12, s42, 0x1d798500
	s_addc_u32 s13, s43, 0
	s_add_u32 s14, s42, 0x1d798600
	s_addc_u32 s15, s43, 0
	s_add_u32 s16, s42, 0x1d798700
	s_addc_u32 s17, s43, 0
	s_add_u32 s18, s42, 0x1d798800
	s_addc_u32 s19, s43, 0
	s_add_u32 s20, s42, 0x1d798900
	s_addc_u32 s21, s43, 0
	s_add_u32 s22, s42, 0x1d798a00
	s_addc_u32 s23, s43, 0
	s_add_u32 s24, s42, 0x1d798b00
	s_addc_u32 s25, s43, 0
	s_add_u32 s26, s42, 0x1d798c00
	s_addc_u32 s27, s43, 0
	s_add_u32 s28, s42, 0x1d798d00
	s_addc_u32 s29, s43, 0
	s_add_u32 s30, s42, 0x1d798e00
	s_addc_u32 s31, s43, 0
	s_add_u32 s34, s42, 0x1d798f00
	s_addc_u32 s35, s43, 0
	s_add_u32 s36, s42, 0x1d799000
	s_addc_u32 s37, s43, 0
	s_add_u32 s38, s42, 0x1d799100
	s_addc_u32 s39, s43, 0
	s_add_u32 s40, s42, 0x1d799200
	s_addc_u32 s41, s43, 0
	s_add_u32 s42, s42, 0x1d799300
	s_addc_u32 s43, s43, 0
	s_branch .LBB0_35

; __device__ __forceinline__ unsigned xb_ld(unsigned* p)              { return __hip_atomic_load(p, __ATOMIC_RELAXED, __HIP_MEMORY_SCOPE_AGENT); }
; __device__ __forceinline__ void xcd_barrier_complete(unsigned* bar, unsigned x, unsigned& nloc, unsigned& nx) {
;     const unsigned G = gridDim.x * gridDim.y * gridDim.z;
;     unsigned sum, cnt, mine, sp = 0u;
;     for (;;) {
;         sum = 0u; cnt = 0u; mine = 0u;
; #pragma unroll
;         for (unsigned j = 0; j < 16; ++j) { const unsigned c = xb_ld(&bar[XB_XCNT(j)]); sum += c; cnt += (c > 0u) ? 1u : 0u; mine = (j == x) ? c : mine; }
; __device__ __forceinline__ void xcd_barrier(const XcdBarrier& b, const bool leader) {
;     asm volatile("s_waitcnt vmcnt(0)" ::: "memory");
;     __syncthreads();
;     if (leader) {
;         unsigned* bar = b.bar;
;         __builtin_amdgcn_s_waitcnt(0);
;         unsigned nloc = b.st[0], nx = b.st[1];
;         if (nloc == 0u) { xcd_barrier_complete(bar, b.x, nloc, nx); b.st[0] = nloc; b.st[1] = nx; }
.LBB0_189:
	s_getreg_b32 s1, hwreg(HW_REG_XCC_ID, 0, 4)
	s_waitcnt vmcnt(0)
	s_waitcnt vmcnt(0)
	s_barrier
	s_mov_b64 s[4:5], exec
	v_readlane_b32 s2, v251, 6
	v_readlane_b32 s3, v251, 7
	s_and_b64 s[2:3], s[4:5], s[2:3]
	s_mov_b64 exec, s[2:3]
	s_cbranch_execz .LBB0_241
	s_add_i32 s2, 0, 0x22000
	v_mov_b32_e32 v2, s2
	s_waitcnt vmcnt(0) expcnt(0) lgkmcnt(0)
	buffer_wbl2 sc1
	ds_read_b32 v4, v2
	s_add_i32 s2, 0, 0x22004
	v_mov_b32_e32 v2, s2
	ds_read_b32 v2, v2
	s_and_b32 s1, s1, 15
	s_waitcnt lgkmcnt(1)
	v_cmp_ne_u32_e32 vcc, 0, v4
	s_cbranch_vccnz .LBB0_205
	s_add_u32 s6, s12, 0x1d798200
	s_addc_u32 s7, s13, 0
	s_add_u32 s8, s12, 0x1d798400
	s_addc_u32 s9, s13, 0
	s_add_u32 s10, s12, 0x1d798500
	s_addc_u32 s11, s13, 0
	s_add_u32 s14, s12, 0x1d798600
	s_addc_u32 s15, s13, 0
	s_add_u32 s16, s12, 0x1d798700
	s_addc_u32 s17, s13, 0
	s_add_u32 s18, s12, 0x1d798800
	s_addc_u32 s19, s13, 0
	s_add_u32 s20, s12, 0x1d798900
	s_addc_u32 s21, s13, 0
	s_add_u32 s22, s12, 0x1d798a00
	s_addc_u32 s23, s13, 0
	s_add_u32 s24, s12, 0x1d798b00
	s_addc_u32 s25, s13, 0
	s_add_u32 s26, s12, 0x1d798c00
	s_addc_u32 s27, s13, 0
	s_add_u32 s28, s12, 0x1d798d00
	s_addc_u32 s29, s13, 0
	s_add_u32 s30, s12, 0x1d798e00
	s_addc_u32 s31, s13, 0
	s_add_u32 s34, s12, 0x1d798f00
	s_addc_u32 s35, s13, 0
	s_add_u32 s36, s12, 0x1d799000
	s_addc_u32 s37, s13, 0
	s_add_u32 s38, s12, 0x1d799100
	s_addc_u32 s39, s13, 0
	s_add_u32 s40, s12, 0x1d799200
	s_addc_u32 s41, s13, 0
	s_mul_i32 s2, s71, s0
	s_add_u32 s42, s12, 0x1d799300
	s_mul_i32 s2, s2, s70
	s_addc_u32 s43, s13, 0
	s_mov_b32 s3, 1
	v_mov_b32_e32 v18, 0
	s_branch .LBB0_193

; __device__ __forceinline__ unsigned xb_ld(unsigned* p)              { return __hip_atomic_load(p, __ATOMIC_RELAXED, __HIP_MEMORY_SCOPE_AGENT); }
; __device__ __forceinline__ void xcd_barrier_complete(unsigned* bar, unsigned x, unsigned& nloc, unsigned& nx) {
;     const unsigned G = gridDim.x * gridDim.y * gridDim.z;
;     unsigned sum, cnt, mine, sp = 0u;
;     for (;;) {
;         sum = 0u; cnt = 0u; mine = 0u;
; #pragma unroll
;         for (unsigned j = 0; j < 16; ++j) { const unsigned c = xb_ld(&bar[XB_XCNT(j)]); sum += c; cnt += (c > 0u) ? 1u : 0u; mine = (j == x) ? c : mine; }
; __device__ __forceinline__ void xcd_barrier(const XcdBarrier& b, const bool leader) {
;     asm volatile("s_waitcnt vmcnt(0)" ::: "memory");
;     __syncthreads();
;     if (leader) {
;         unsigned* bar = b.bar;
;         __builtin_amdgcn_s_waitcnt(0);
;         unsigned nloc = b.st[0], nx = b.st[1];
;         if (nloc == 0u) { xcd_barrier_complete(bar, b.x, nloc, nx); b.st[0] = nloc; b.st[1] = nx; }
.LBB0_292:
	s_getreg_b32 s1, hwreg(HW_REG_XCC_ID, 0, 4)
	s_waitcnt vmcnt(0)
	s_waitcnt lgkmcnt(0)
	s_barrier
	s_mov_b64 s[6:7], exec
	v_readlane_b32 s2, v251, 6
	v_readlane_b32 s3, v251, 7
	s_and_b64 s[2:3], s[6:7], s[2:3]
	s_mov_b64 exec, s[2:3]
	s_cbranch_execz .LBB0_344
	s_add_i32 s2, 0, 0x22000
	v_mov_b32_e32 v2, s2
	s_waitcnt vmcnt(0) expcnt(0) lgkmcnt(0)
	buffer_wbl2 sc1
	ds_read_b32 v4, v2
	s_add_i32 s2, 0, 0x22004
	v_mov_b32_e32 v2, s2
	ds_read_b32 v2, v2
	s_and_b32 s1, s1, 15
	s_waitcnt lgkmcnt(1)
	v_cmp_ne_u32_e32 vcc, 0, v4
	s_cbranch_vccnz .LBB0_308
	s_add_u32 s8, s4, 0x1d798200
	s_addc_u32 s9, s5, 0
	s_add_u32 s10, s4, 0x1d798400
	s_addc_u32 s11, s5, 0
	s_add_u32 s12, s4, 0x1d798500
	s_addc_u32 s13, s5, 0
	s_add_u32 s14, s4, 0x1d798600
	s_addc_u32 s15, s5, 0
	s_add_u32 s16, s4, 0x1d798700
	s_addc_u32 s17, s5, 0
	s_add_u32 s18, s4, 0x1d798800
	s_addc_u32 s19, s5, 0
	s_add_u32 s20, s4, 0x1d798900
	s_addc_u32 s21, s5, 0
	s_add_u32 s22, s4, 0x1d798a00
	s_addc_u32 s23, s5, 0
	s_add_u32 s24, s4, 0x1d798b00
	s_addc_u32 s25, s5, 0
	s_add_u32 s26, s4, 0x1d798c00
	s_addc_u32 s27, s5, 0
	s_add_u32 s28, s4, 0x1d798d00
	s_addc_u32 s29, s5, 0
	s_add_u32 s30, s4, 0x1d798e00
	s_addc_u32 s31, s5, 0
	s_add_u32 s34, s4, 0x1d798f00
	s_addc_u32 s35, s5, 0
	s_add_u32 s36, s4, 0x1d799000
	s_addc_u32 s37, s5, 0
	s_add_u32 s38, s4, 0x1d799100
	s_addc_u32 s39, s5, 0
	s_add_u32 s40, s4, 0x1d799200
	s_addc_u32 s41, s5, 0
	s_mul_i32 s2, s71, s0
	s_add_u32 s42, s4, 0x1d799300
	s_mul_i32 s2, s2, s70
	s_addc_u32 s43, s5, 0
	s_mov_b32 s3, 1
	v_mov_b32_e32 v18, 0
	s_branch .LBB0_296

; __device__ __forceinline__ unsigned xb_ld(unsigned* p)              { return __hip_atomic_load(p, __ATOMIC_RELAXED, __HIP_MEMORY_SCOPE_AGENT); }
; __device__ __forceinline__ void xcd_barrier_complete(unsigned* bar, unsigned x, unsigned& nloc, unsigned& nx) {
;     const unsigned G = gridDim.x * gridDim.y * gridDim.z;
;     unsigned sum, cnt, mine, sp = 0u;
;     for (;;) {
;         sum = 0u; cnt = 0u; mine = 0u;
; #pragma unroll
;         for (unsigned j = 0; j < 16; ++j) { const unsigned c = xb_ld(&bar[XB_XCNT(j)]); sum += c; cnt += (c > 0u) ? 1u : 0u; mine = (j == x) ? c : mine; }
; __device__ __forceinline__ void xcd_barrier(const XcdBarrier& b, const bool leader) {
;     asm volatile("s_waitcnt vmcnt(0)" ::: "memory");
;     __syncthreads();
;     if (leader) {
;         unsigned* bar = b.bar;
;         __builtin_amdgcn_s_waitcnt(0);
;         unsigned nloc = b.st[0], nx = b.st[1];
;         if (nloc == 0u) { xcd_barrier_complete(bar, b.x, nloc, nx); b.st[0] = nloc; b.st[1] = nx; }
.LBB0_452:
	s_getreg_b32 s2, hwreg(HW_REG_XCC_ID, 0, 4)
	s_waitcnt vmcnt(0)
	v_readlane_b32 s8, v251, 6
	v_readlane_b32 s9, v251, 7
	s_barrier
	s_and_saveexec_b64 s[6:7], s[8:9]
	s_xor_b64 s[8:9], exec, s[6:7]
	s_cbranch_execz .LBB0_505
	v_readlane_b32 s0, v251, 51
	s_waitcnt vmcnt(0) expcnt(0) lgkmcnt(0)
	buffer_wbl2 sc1
	s_and_b32 s2, s2, 15
	v_mov_b32_e32 v2, s0
	ds_read_b32 v5, v2
	v_readlane_b32 s0, v251, 52
	s_waitcnt lgkmcnt(0)
	v_cmp_ne_u32_e32 vcc, 0, v5
	v_mov_b32_e32 v2, s0
	ds_read_b32 v4, v2
	s_cbranch_vccnz .LBB0_468
	s_add_u32 s10, s18, 0x1d798200
	s_addc_u32 s11, s19, 0
	s_add_u32 s12, s18, 0x1d798400
	s_addc_u32 s13, s19, 0
	s_add_u32 s14, s18, 0x1d798500
	s_addc_u32 s15, s19, 0
	s_add_u32 s16, s18, 0x1d798600
	s_addc_u32 s17, s19, 0
	s_add_u32 s20, s18, 0x1d798700
	s_addc_u32 s21, s19, 0
	s_add_u32 s22, s18, 0x1d798800
	s_addc_u32 s23, s19, 0
	s_add_u32 s24, s18, 0x1d798900
	s_addc_u32 s25, s19, 0
	s_add_u32 s26, s18, 0x1d798a00
	s_addc_u32 s27, s19, 0
	s_add_u32 s28, s18, 0x1d798b00
	s_addc_u32 s29, s19, 0
	s_add_u32 s30, s18, 0x1d798c00
	s_addc_u32 s31, s19, 0
	s_add_u32 s34, s18, 0x1d798d00
	s_addc_u32 s35, s19, 0
	s_add_u32 s36, s18, 0x1d798e00
	s_addc_u32 s37, s19, 0
	s_add_u32 s38, s18, 0x1d798f00
	s_addc_u32 s39, s19, 0
	s_add_u32 s40, s18, 0x1d799000
	s_addc_u32 s41, s19, 0
	s_add_u32 s42, s18, 0x1d799100
	s_addc_u32 s43, s19, 0
	s_add_u32 s44, s18, 0x1d799200
	s_addc_u32 s45, s19, 0
	s_add_u32 s46, s18, 0x1d799300
	s_addc_u32 s47, s19, 0
	s_mov_b32 s3, 1
	s_branch .LBB0_456

; __device__ __forceinline__ unsigned xb_ld(unsigned* p)              { return __hip_atomic_load(p, __ATOMIC_RELAXED, __HIP_MEMORY_SCOPE_AGENT); }
; __device__ __forceinline__ void xcd_barrier_complete(unsigned* bar, unsigned x, unsigned& nloc, unsigned& nx) {
;     const unsigned G = gridDim.x * gridDim.y * gridDim.z;
;     unsigned sum, cnt, mine, sp = 0u;
;     for (;;) {
;         sum = 0u; cnt = 0u; mine = 0u;
; #pragma unroll
;         for (unsigned j = 0; j < 16; ++j) { const unsigned c = xb_ld(&bar[XB_XCNT(j)]); sum += c; cnt += (c > 0u) ? 1u : 0u; mine = (j == x) ? c : mine; }
; __device__ __forceinline__ void xcd_barrier(const XcdBarrier& b, const bool leader) {
;     asm volatile("s_waitcnt vmcnt(0)" ::: "memory");
;     __syncthreads();
;     if (leader) {
;         unsigned* bar = b.bar;
;         __builtin_amdgcn_s_waitcnt(0);
;         unsigned nloc = b.st[0], nx = b.st[1];
;         if (nloc == 0u) { xcd_barrier_complete(bar, b.x, nloc, nx); b.st[0] = nloc; b.st[1] = nx; }
.LBB0_564:
	s_getreg_b32 s2, hwreg(HW_REG_XCC_ID, 0, 4)
	s_waitcnt vmcnt(0)
	s_barrier
	s_mov_b64 s[4:5], exec
	v_readlane_b32 s6, v251, 6
	v_readlane_b32 s7, v251, 7
	v_readlane_b32 s50, v250, 7
	s_and_b64 s[6:7], s[4:5], s[6:7]
	s_movk_i32 s33, 0x100
	v_readlane_b32 s51, v250, 8
	s_mov_b64 exec, s[6:7]
	s_cbranch_execz .LBB0_616
	v_readlane_b32 s0, v251, 51
	s_waitcnt vmcnt(0) expcnt(0) lgkmcnt(0)
	buffer_wbl2 sc1
	s_and_b32 s2, s2, 15
	v_mov_b32_e32 v2, s0
	ds_read_b32 v5, v2
	v_readlane_b32 s0, v251, 52
	s_waitcnt lgkmcnt(0)
	v_cmp_ne_u32_e32 vcc, 0, v5
	v_mov_b32_e32 v2, s0
	ds_read_b32 v4, v2
	s_cbranch_vccnz .LBB0_580
	s_add_u32 s8, s50, 0x1d798200
	s_addc_u32 s9, s51, 0
	s_add_u32 s10, s50, 0x1d798400
	s_addc_u32 s11, s51, 0
	s_add_u32 s12, s50, 0x1d798500
	s_addc_u32 s13, s51, 0
	s_add_u32 s14, s50, 0x1d798600
	s_addc_u32 s15, s51, 0
	s_add_u32 s16, s50, 0x1d798700
	s_addc_u32 s17, s51, 0
	s_add_u32 s18, s50, 0x1d798800
	s_addc_u32 s19, s51, 0
	s_add_u32 s20, s50, 0x1d798900
	s_addc_u32 s21, s51, 0
	s_add_u32 s22, s50, 0x1d798a00
	s_addc_u32 s23, s51, 0
	s_add_u32 s24, s50, 0x1d798b00
	s_addc_u32 s25, s51, 0
	s_add_u32 s26, s50, 0x1d798c00
	s_addc_u32 s27, s51, 0
	s_add_u32 s28, s50, 0x1d798d00
	s_addc_u32 s29, s51, 0
	s_add_u32 s30, s50, 0x1d798e00
	s_addc_u32 s31, s51, 0
	s_add_u32 s34, s50, 0x1d798f00
	s_addc_u32 s35, s51, 0
	s_add_u32 s36, s50, 0x1d799000
	s_addc_u32 s37, s51, 0
	s_add_u32 s38, s50, 0x1d799100
	s_addc_u32 s39, s51, 0
	s_add_u32 s40, s50, 0x1d799200
	s_addc_u32 s41, s51, 0
	s_add_u32 s42, s50, 0x1d799300
	s_addc_u32 s43, s51, 0
	s_mov_b32 s3, 1
	s_branch .LBB0_568

; __device__ __forceinline__ unsigned xb_ld(unsigned* p)              { return __hip_atomic_load(p, __ATOMIC_RELAXED, __HIP_MEMORY_SCOPE_AGENT); }
; __device__ __forceinline__ void xcd_barrier_complete(unsigned* bar, unsigned x, unsigned& nloc, unsigned& nx) {
;     const unsigned G = gridDim.x * gridDim.y * gridDim.z;
;     unsigned sum, cnt, mine, sp = 0u;
;     for (;;) {
;         sum = 0u; cnt = 0u; mine = 0u;
; #pragma unroll
;         for (unsigned j = 0; j < 16; ++j) { const unsigned c = xb_ld(&bar[XB_XCNT(j)]); sum += c; cnt += (c > 0u) ? 1u : 0u; mine = (j == x) ? c : mine; }
; __device__ __forceinline__ void xcd_barrier(const XcdBarrier& b, const bool leader) {
;     asm volatile("s_waitcnt vmcnt(0)" ::: "memory");
;     __syncthreads();
;     if (leader) {
;         unsigned* bar = b.bar;
;         __builtin_amdgcn_s_waitcnt(0);
;         unsigned nloc = b.st[0], nx = b.st[1];
;         if (nloc == 0u) { xcd_barrier_complete(bar, b.x, nloc, nx); b.st[0] = nloc; b.st[1] = nx; }
.LBB0_642:
	s_or_b64 exec, exec, s[12:13]
	s_getreg_b32 s2, hwreg(HW_REG_XCC_ID, 0, 4)
	s_waitcnt vmcnt(0)
	s_barrier
	s_mov_b64 s[8:9], exec
	v_readlane_b32 s6, v251, 6
	v_readlane_b32 s7, v251, 7
	s_and_b64 s[6:7], s[8:9], s[6:7]
	s_mov_b64 exec, s[6:7]
	s_cbranch_execz .LBB0_694
	v_readlane_b32 s0, v251, 51
	s_waitcnt vmcnt(0) expcnt(0) lgkmcnt(0)
	buffer_wbl2 sc1
	s_load_dwordx4 s[12:15], s[90:91], 0xa8
	v_mov_b32_e32 v2, s0
	ds_read_b32 v5, v2
	v_readlane_b32 s0, v251, 52
	s_waitcnt lgkmcnt(0)
	s_add_u32 s4, s14, s4
	v_mov_b32_e32 v2, s0
	ds_read_b32 v4, v2
	v_cmp_ne_u32_e32 vcc, 0, v5
	s_addc_u32 s5, s15, s5
	s_and_b32 s2, s2, 15
	s_cbranch_vccnz .LBB0_658
	s_add_u32 s10, s4, 0x1d798200
	s_addc_u32 s11, s5, 0
	s_add_u32 s12, s4, 0x1d798400
	s_addc_u32 s13, s5, 0
	s_add_u32 s14, s4, 0x1d798500
	s_addc_u32 s15, s5, 0
	s_add_u32 s16, s4, 0x1d798600
	s_addc_u32 s17, s5, 0
	s_add_u32 s18, s4, 0x1d798700
	s_addc_u32 s19, s5, 0
	s_add_u32 s20, s4, 0x1d798800
	s_addc_u32 s21, s5, 0
	s_add_u32 s22, s4, 0x1d798900
	s_addc_u32 s23, s5, 0
	s_add_u32 s24, s4, 0x1d798a00
	s_addc_u32 s25, s5, 0
	s_add_u32 s26, s4, 0x1d798b00
	s_addc_u32 s27, s5, 0
	s_add_u32 s28, s4, 0x1d798c00
	s_addc_u32 s29, s5, 0
	s_add_u32 s30, s4, 0x1d798d00
	s_addc_u32 s31, s5, 0
	s_add_u32 s34, s4, 0x1d798e00
	s_addc_u32 s35, s5, 0
	s_add_u32 s36, s4, 0x1d798f00
	s_addc_u32 s37, s5, 0
	s_add_u32 s38, s4, 0x1d799000
	s_addc_u32 s39, s5, 0
	s_add_u32 s40, s4, 0x1d799100
	s_addc_u32 s41, s5, 0
	s_add_u32 s42, s4, 0x1d799200
	s_addc_u32 s43, s5, 0
	s_add_u32 s44, s4, 0x1d799300
	s_addc_u32 s45, s5, 0
	s_mov_b32 s3, 1
	s_branch .LBB0_646

; __device__ __forceinline__ unsigned xb_ld(unsigned* p)              { return __hip_atomic_load(p, __ATOMIC_RELAXED, __HIP_MEMORY_SCOPE_AGENT); }
; __device__ __forceinline__ void xcd_barrier_complete(unsigned* bar, unsigned x, unsigned& nloc, unsigned& nx) {
;     const unsigned G = gridDim.x * gridDim.y * gridDim.z;
;     unsigned sum, cnt, mine, sp = 0u;
;     for (;;) {
;         sum = 0u; cnt = 0u; mine = 0u;
; #pragma unroll
;         for (unsigned j = 0; j < 16; ++j) { const unsigned c = xb_ld(&bar[XB_XCNT(j)]); sum += c; cnt += (c > 0u) ? 1u : 0u; mine = (j == x) ? c : mine; }
; __device__ __forceinline__ void xcd_barrier(const XcdBarrier& b, const bool leader) {
;     asm volatile("s_waitcnt vmcnt(0)" ::: "memory");
;     __syncthreads();
;     if (leader) {
;         unsigned* bar = b.bar;
;         __builtin_amdgcn_s_waitcnt(0);
;         unsigned nloc = b.st[0], nx = b.st[1];
;         if (nloc == 0u) { xcd_barrier_complete(bar, b.x, nloc, nx); b.st[0] = nloc; b.st[1] = nx; }
.LBB0_699:
	s_getreg_b32 s2, hwreg(HW_REG_XCC_ID, 0, 4)
	s_waitcnt vmcnt(0)
	s_barrier
	s_mov_b64 s[8:9], exec
	v_readlane_b32 s6, v251, 6
	v_readlane_b32 s7, v251, 7
	s_and_b64 s[6:7], s[8:9], s[6:7]
	s_mov_b64 exec, s[6:7]
	s_cbranch_execz .LBB0_751
	v_readlane_b32 s0, v251, 51
	s_waitcnt vmcnt(0) expcnt(0) lgkmcnt(0)
	buffer_wbl2 sc1
	s_and_b32 s2, s2, 15
	v_mov_b32_e32 v2, s0
	ds_read_b32 v5, v2
	v_readlane_b32 s0, v251, 52
	s_waitcnt lgkmcnt(0)
	v_cmp_ne_u32_e32 vcc, 0, v5
	v_mov_b32_e32 v2, s0
	ds_read_b32 v4, v2
	s_cbranch_vccnz .LBB0_715
	s_add_u32 s10, s4, 0x1d798200
	s_addc_u32 s11, s5, 0
	s_add_u32 s12, s4, 0x1d798400
	s_addc_u32 s13, s5, 0
	s_add_u32 s14, s4, 0x1d798500
	s_addc_u32 s15, s5, 0
	s_add_u32 s16, s4, 0x1d798600
	s_addc_u32 s17, s5, 0
	s_add_u32 s18, s4, 0x1d798700
	s_addc_u32 s19, s5, 0
	s_add_u32 s20, s4, 0x1d798800
	s_addc_u32 s21, s5, 0
	s_add_u32 s22, s4, 0x1d798900
	s_addc_u32 s23, s5, 0
	s_add_u32 s24, s4, 0x1d798a00
	s_addc_u32 s25, s5, 0
	s_add_u32 s26, s4, 0x1d798b00
	s_addc_u32 s27, s5, 0
	s_add_u32 s28, s4, 0x1d798c00
	s_addc_u32 s29, s5, 0
	s_add_u32 s30, s4, 0x1d798d00
	s_addc_u32 s31, s5, 0
	s_add_u32 s34, s4, 0x1d798e00
	s_addc_u32 s35, s5, 0
	s_add_u32 s36, s4, 0x1d798f00
	s_addc_u32 s37, s5, 0
	s_add_u32 s38, s4, 0x1d799000
	s_addc_u32 s39, s5, 0
	s_add_u32 s40, s4, 0x1d799100
	s_addc_u32 s41, s5, 0
	s_add_u32 s42, s4, 0x1d799200
	s_addc_u32 s43, s5, 0
	s_add_u32 s44, s4, 0x1d799300
	s_addc_u32 s45, s5, 0
	s_mov_b32 s3, 1
	s_branch .LBB0_703

; __device__ __forceinline__ unsigned xb_ld(unsigned* p)              { return __hip_atomic_load(p, __ATOMIC_RELAXED, __HIP_MEMORY_SCOPE_AGENT); }
; __device__ __forceinline__ void xcd_barrier_complete(unsigned* bar, unsigned x, unsigned& nloc, unsigned& nx) {
;     const unsigned G = gridDim.x * gridDim.y * gridDim.z;
;     unsigned sum, cnt, mine, sp = 0u;
;     for (;;) {
;         sum = 0u; cnt = 0u; mine = 0u;
; #pragma unroll
;         for (unsigned j = 0; j < 16; ++j) { const unsigned c = xb_ld(&bar[XB_XCNT(j)]); sum += c; cnt += (c > 0u) ? 1u : 0u; mine = (j == x) ? c : mine; }
; __device__ __forceinline__ void xcd_barrier(const XcdBarrier& b, const bool leader) {
;     asm volatile("s_waitcnt vmcnt(0)" ::: "memory");
;     __syncthreads();
;     if (leader) {
;         unsigned* bar = b.bar;
;         __builtin_amdgcn_s_waitcnt(0);
;         unsigned nloc = b.st[0], nx = b.st[1];
;         if (nloc == 0u) { xcd_barrier_complete(bar, b.x, nloc, nx); b.st[0] = nloc; b.st[1] = nx; }
.LBB0_803:
	s_getreg_b32 s2, hwreg(HW_REG_XCC_ID, 0, 4)
	s_waitcnt vmcnt(0)
	s_barrier
	s_mov_b64 s[4:5], exec
	v_readlane_b32 s6, v251, 6
	v_readlane_b32 s7, v251, 7
	s_and_b64 s[6:7], s[4:5], s[6:7]
	s_mov_b64 exec, s[6:7]
	s_cbranch_execz .LBB0_855
	v_readlane_b32 s0, v251, 51
	s_waitcnt vmcnt(0) expcnt(0) lgkmcnt(0)
	buffer_wbl2 sc1
	s_and_b32 s2, s2, 15
	v_mov_b32_e32 v2, s0
	ds_read_b32 v5, v2
	v_readlane_b32 s0, v251, 52
	s_waitcnt lgkmcnt(0)
	v_cmp_ne_u32_e32 vcc, 0, v5
	v_mov_b32_e32 v2, s0
	ds_read_b32 v4, v2
	s_cbranch_vccnz .LBB0_819
	s_add_u32 s14, s12, 0x1d798200
	s_addc_u32 s15, s13, 0
	s_add_u32 s16, s12, 0x1d798400
	s_addc_u32 s17, s13, 0
	s_add_u32 s18, s12, 0x1d798500
	s_addc_u32 s19, s13, 0
	s_add_u32 s20, s12, 0x1d798600
	s_addc_u32 s21, s13, 0
	s_add_u32 s22, s12, 0x1d798700
	s_addc_u32 s23, s13, 0
	s_add_u32 s24, s12, 0x1d798800
	s_addc_u32 s25, s13, 0
	s_add_u32 s26, s12, 0x1d798900
	s_addc_u32 s27, s13, 0
	s_add_u32 s28, s12, 0x1d798a00
	s_addc_u32 s29, s13, 0
	s_add_u32 s30, s12, 0x1d798b00
	s_addc_u32 s31, s13, 0
	s_add_u32 s34, s12, 0x1d798c00
	s_addc_u32 s35, s13, 0
	s_add_u32 s36, s12, 0x1d798d00
	s_addc_u32 s37, s13, 0
	s_add_u32 s38, s12, 0x1d798e00
	s_addc_u32 s39, s13, 0
	s_add_u32 s40, s12, 0x1d798f00
	s_addc_u32 s41, s13, 0
	s_add_u32 s42, s12, 0x1d799000
	s_addc_u32 s43, s13, 0
	s_add_u32 s44, s12, 0x1d799100
	s_addc_u32 s45, s13, 0
	s_add_u32 s46, s12, 0x1d799200
	s_addc_u32 s47, s13, 0
	s_add_u32 s48, s12, 0x1d799300
	s_addc_u32 s49, s13, 0
	s_mov_b32 s3, 1
	s_branch .LBB0_807

; __device__ __forceinline__ unsigned xb_ld(unsigned* p)              { return __hip_atomic_load(p, __ATOMIC_RELAXED, __HIP_MEMORY_SCOPE_AGENT); }
; __device__ __forceinline__ void xcd_barrier_complete(unsigned* bar, unsigned x, unsigned& nloc, unsigned& nx) {
;     const unsigned G = gridDim.x * gridDim.y * gridDim.z;
;     unsigned sum, cnt, mine, sp = 0u;
;     for (;;) {
;         sum = 0u; cnt = 0u; mine = 0u;
; #pragma unroll
;         for (unsigned j = 0; j < 16; ++j) { const unsigned c = xb_ld(&bar[XB_XCNT(j)]); sum += c; cnt += (c > 0u) ? 1u : 0u; mine = (j == x) ? c : mine; }
; __device__ __forceinline__ void xcd_barrier(const XcdBarrier& b, const bool leader) {
;     asm volatile("s_waitcnt vmcnt(0)" ::: "memory");
;     __syncthreads();
;     if (leader) {
;         unsigned* bar = b.bar;
;         __builtin_amdgcn_s_waitcnt(0);
;         unsigned nloc = b.st[0], nx = b.st[1];
;         if (nloc == 0u) { xcd_barrier_complete(bar, b.x, nloc, nx); b.st[0] = nloc; b.st[1] = nx; }
.LBB0_1012:
	s_getreg_b32 s2, hwreg(HW_REG_XCC_ID, 0, 4)
	s_waitcnt vmcnt(0)
	s_waitcnt lgkmcnt(0)
	s_barrier
	s_mov_b64 s[4:5], exec
	v_readlane_b32 s6, v251, 6
	v_readlane_b32 s7, v251, 7
	s_and_b64 s[6:7], s[4:5], s[6:7]
	s_mov_b64 exec, s[6:7]
	s_cbranch_execz .LBB0_346
	v_readlane_b32 s0, v251, 51
	s_waitcnt vmcnt(0) expcnt(0) lgkmcnt(0)
	buffer_wbl2 sc1
	s_and_b32 s2, s2, 15
	v_mov_b32_e32 v2, s0
	ds_read_b32 v5, v2
	v_readlane_b32 s0, v251, 52
	s_waitcnt lgkmcnt(0)
	v_cmp_ne_u32_e32 vcc, 0, v5
	v_mov_b32_e32 v2, s0
	ds_read_b32 v4, v2
	s_cbranch_vccnz .LBB0_1028
	s_add_u32 s10, s18, 0x1d798200
	s_addc_u32 s11, s19, 0
	s_add_u32 s12, s18, 0x1d798400
	s_addc_u32 s13, s19, 0
	s_add_u32 s14, s18, 0x1d798500
	s_addc_u32 s15, s19, 0
	s_add_u32 s16, s18, 0x1d798600
	s_addc_u32 s17, s19, 0
	s_add_u32 s20, s18, 0x1d798700
	s_addc_u32 s21, s19, 0
	s_add_u32 s22, s18, 0x1d798800
	s_addc_u32 s23, s19, 0
	s_add_u32 s24, s18, 0x1d798900
	s_addc_u32 s25, s19, 0
	s_add_u32 s26, s18, 0x1d798a00
	s_addc_u32 s27, s19, 0
	s_add_u32 s28, s18, 0x1d798b00
	s_addc_u32 s29, s19, 0
	s_add_u32 s30, s18, 0x1d798c00
	s_addc_u32 s31, s19, 0
	s_add_u32 s34, s18, 0x1d798d00
	s_addc_u32 s35, s19, 0
	s_add_u32 s36, s18, 0x1d798e00
	s_addc_u32 s37, s19, 0
	s_add_u32 s38, s18, 0x1d798f00
	s_addc_u32 s39, s19, 0
	s_add_u32 s40, s18, 0x1d799000
	s_addc_u32 s41, s19, 0
	s_add_u32 s42, s18, 0x1d799100
	s_addc_u32 s43, s19, 0
	s_add_u32 s44, s18, 0x1d799200
	s_addc_u32 s45, s19, 0
	s_add_u32 s46, s18, 0x1d799300
	s_addc_u32 s47, s19, 0
	s_mov_b32 s3, 1
	s_branch .LBB0_1016

; __device__ __forceinline__ unsigned xb_ld(unsigned* p)              { return __hip_atomic_load(p, __ATOMIC_RELAXED, __HIP_MEMORY_SCOPE_AGENT); }
; __device__ __forceinline__ void xcd_barrier_complete(unsigned* bar, unsigned x, unsigned& nloc, unsigned& nx) {
;     const unsigned G = gridDim.x * gridDim.y * gridDim.z;
;     unsigned sum, cnt, mine, sp = 0u;
;     for (;;) {
;         sum = 0u; cnt = 0u; mine = 0u;
; #pragma unroll
;         for (unsigned j = 0; j < 16; ++j) { const unsigned c = xb_ld(&bar[XB_XCNT(j)]); sum += c; cnt += (c > 0u) ? 1u : 0u; mine = (j == x) ? c : mine; }
; __device__ __forceinline__ void xcd_barrier(const XcdBarrier& b, const bool leader) {
;     asm volatile("s_waitcnt vmcnt(0)" ::: "memory");
;     __syncthreads();
;     if (leader) {
;         unsigned* bar = b.bar;
;         __builtin_amdgcn_s_waitcnt(0);
;         unsigned nloc = b.st[0], nx = b.st[1];
;         if (nloc == 0u) { xcd_barrier_complete(bar, b.x, nloc, nx); b.st[0] = nloc; b.st[1] = nx; }
.LBB0_1097:
	s_or_b64 exec, exec, s[4:5]
	s_barrier
	s_getreg_b32 s0, hwreg(HW_REG_XCC_ID, 0, 4)
	s_waitcnt vmcnt(0)
	s_barrier
	s_mov_b64 s[4:5], exec
	v_readlane_b32 s2, v251, 6
	v_readlane_b32 s3, v251, 7
	s_and_b64 s[2:3], s[4:5], s[2:3]
	s_mov_b64 exec, s[2:3]
	s_cbranch_execz .LBB0_1149
	s_add_i32 s1, 0, 0x22000
	v_mov_b32_e32 v0, s1
	s_waitcnt vmcnt(0) expcnt(0) lgkmcnt(0)
	buffer_wbl2 sc1
	ds_read_b32 v2, v0
	s_add_i32 s1, 0, 0x22004
	v_mov_b32_e32 v0, s1
	ds_read_b32 v0, v0
	s_and_b32 s0, s0, 15
	s_waitcnt lgkmcnt(1)
	v_cmp_ne_u32_e32 vcc, 0, v2
	s_cbranch_vccnz .LBB0_1113
	s_add_u32 s6, s18, 0x1d798200
	s_addc_u32 s7, s19, 0
	s_add_u32 s10, s18, 0x1d798400
	s_addc_u32 s11, s19, 0
	s_add_u32 s12, s18, 0x1d798500
	s_addc_u32 s13, s19, 0
	s_add_u32 s14, s18, 0x1d798600
	s_addc_u32 s15, s19, 0
	s_add_u32 s16, s18, 0x1d798700
	s_addc_u32 s17, s19, 0
	s_add_u32 s20, s18, 0x1d798800
	s_addc_u32 s21, s19, 0
	s_add_u32 s22, s18, 0x1d798900
	s_addc_u32 s23, s19, 0
	s_add_u32 s24, s18, 0x1d798a00
	s_addc_u32 s25, s19, 0
	s_add_u32 s26, s18, 0x1d798b00
	s_addc_u32 s27, s19, 0
	s_add_u32 s28, s18, 0x1d798c00
	s_addc_u32 s29, s19, 0
	s_add_u32 s30, s18, 0x1d798d00
	s_addc_u32 s31, s19, 0
	s_add_u32 s34, s18, 0x1d798e00
	s_addc_u32 s35, s19, 0
	s_add_u32 s36, s18, 0x1d798f00
	s_addc_u32 s37, s19, 0
	s_add_u32 s38, s18, 0x1d799000
	s_addc_u32 s39, s19, 0
	s_add_u32 s40, s18, 0x1d799100
	s_addc_u32 s41, s19, 0
	s_add_u32 s42, s18, 0x1d799200
	s_addc_u32 s43, s19, 0
	s_add_u32 s44, s18, 0x1d799300
	s_addc_u32 s45, s19, 0
	s_mov_b32 s1, 1
	v_mov_b32_e32 v16, 0
	s_branch .LBB0_1101

; __device__ __forceinline__ unsigned xb_ld(unsigned* p)              { return __hip_atomic_load(p, __ATOMIC_RELAXED, __HIP_MEMORY_SCOPE_AGENT); }
; __device__ __forceinline__ void xcd_barrier_complete(unsigned* bar, unsigned x, unsigned& nloc, unsigned& nx) {
;     const unsigned G = gridDim.x * gridDim.y * gridDim.z;
;     unsigned sum, cnt, mine, sp = 0u;
;     for (;;) {
;         sum = 0u; cnt = 0u; mine = 0u;
; #pragma unroll
;         for (unsigned j = 0; j < 16; ++j) { const unsigned c = xb_ld(&bar[XB_XCNT(j)]); sum += c; cnt += (c > 0u) ? 1u : 0u; mine = (j == x) ? c : mine; }
; __device__ __forceinline__ void xcd_barrier(const XcdBarrier& b, const bool leader) {
;     asm volatile("s_waitcnt vmcnt(0)" ::: "memory");
;     __syncthreads();
;     if (leader) {
;         unsigned* bar = b.bar;
;         __builtin_amdgcn_s_waitcnt(0);
;         unsigned nloc = b.st[0], nx = b.st[1];
;         if (nloc == 0u) { xcd_barrier_complete(bar, b.x, nloc, nx); b.st[0] = nloc; b.st[1] = nx; }
.LBB0_1180:
	s_getreg_b32 s0, hwreg(HW_REG_XCC_ID, 0, 4)
	s_waitcnt vmcnt(0)
	s_barrier
	s_mov_b64 s[2:3], exec
	v_readlane_b32 s6, v251, 6
	v_readlane_b32 s7, v251, 7
	s_and_b64 s[6:7], s[2:3], s[6:7]
	s_mov_b64 exec, s[6:7]
	s_cbranch_execz .LBB0_1232
	s_add_i32 s1, 0, 0x22000
	v_mov_b32_e32 v0, s1
	s_waitcnt vmcnt(0) expcnt(0) lgkmcnt(0)
	buffer_wbl2 sc1
	ds_read_b32 v2, v0
	s_add_i32 s1, 0, 0x22004
	v_mov_b32_e32 v0, s1
	ds_read_b32 v0, v0
	s_and_b32 s0, s0, 15
	s_waitcnt lgkmcnt(1)
	v_cmp_ne_u32_e32 vcc, 0, v2
	s_cbranch_vccnz .LBB0_1196
	s_add_u32 s6, s4, 0x1d798200
	s_addc_u32 s7, s5, 0
	s_add_u32 s8, s4, 0x1d798400
	s_addc_u32 s9, s5, 0
	s_add_u32 s10, s4, 0x1d798500
	s_addc_u32 s11, s5, 0
	s_add_u32 s12, s4, 0x1d798600
	s_addc_u32 s13, s5, 0
	s_add_u32 s14, s4, 0x1d798700
	s_addc_u32 s15, s5, 0
	s_add_u32 s16, s4, 0x1d798800
	s_addc_u32 s17, s5, 0
	s_add_u32 s18, s4, 0x1d798900
	s_addc_u32 s19, s5, 0
	s_add_u32 s20, s4, 0x1d798a00
	s_addc_u32 s21, s5, 0
	s_add_u32 s22, s4, 0x1d798b00
	s_addc_u32 s23, s5, 0
	s_add_u32 s24, s4, 0x1d798c00
	s_addc_u32 s25, s5, 0
	s_add_u32 s26, s4, 0x1d798d00
	s_addc_u32 s27, s5, 0
	s_add_u32 s28, s4, 0x1d798e00
	s_addc_u32 s29, s5, 0
	s_add_u32 s30, s4, 0x1d798f00
	s_addc_u32 s31, s5, 0
	s_add_u32 s34, s4, 0x1d799000
	s_addc_u32 s35, s5, 0
	s_add_u32 s36, s4, 0x1d799100
	s_addc_u32 s37, s5, 0
	s_add_u32 s38, s4, 0x1d799200
	s_addc_u32 s39, s5, 0
	s_add_u32 s40, s4, 0x1d799300
	s_addc_u32 s41, s5, 0
	s_mov_b32 s1, 1
	v_mov_b32_e32 v16, 0
	s_branch .LBB0_1184
